# normmod row loops: all four row loads in flight at once (which=1,2) and the wave-wide sum of squares reduced with DPP instead of six LDS permute round trips (all three)
# speedup vs baseline: 1.1080x; 1.0010x over previous
; DI void normmod_phase(const P& p, int layer, int which, int nrows, bool first, int vb, int nvb) {
;     ...
;     f32x4v v[4];
;     float ss = 0.f;
; #pragma unroll
;     for (int i = 0; i < 4; ++i) {
;       v[i] = *(const f32x4v*)(src + i * 256 + lane * 4);
;       ss += v[i].x * v[i].x + v[i].y * v[i].y + v[i].z * v[i].z + v[i].w * v[i].w;
;     }
;     ss = wave_sum(ss);
;     const float rinv = rsqrtf(ss * (1.f / 1024.f) + EPS);
.LBB0_140:
	s_or_b64 exec, exec, s[38:39]
	v_mov_b32_e32 v75, v96
	v_lshl_add_u64 v[32:33], v[32:33], 0, v[74:75]
	global_load_dwordx4 v[44:47], v[32:33], off
	global_load_dwordx4 v[36:39], v[32:33], off offset:1024
	global_load_dwordx4 v[40:43], v[32:33], off offset:2048
	s_nop 0
	global_load_dwordx4 v[32:35], v[32:33], off offset:3072
	s_and_b64 vcc, exec, s[0:1]
	s_waitcnt vmcnt(3)
	v_mov_b32_e32 v86, v45
	s_waitcnt vmcnt(2)
	v_mov_b32_e32 v87, v37
	v_mov_b32_e32 v76, v44
	v_mov_b32_e32 v77, v36
	s_waitcnt vmcnt(1)
	v_mov_b32_e32 v94, v41
	s_waitcnt vmcnt(0)
	v_mov_b32_e32 v95, v33
	v_pk_mul_f32 v[86:87], v[86:87], v[86:87]
	v_mov_b32_e32 v88, v46
	v_mov_b32_e32 v89, v38
	v_mov_b32_e32 v92, v40
	v_mov_b32_e32 v93, v32
	v_pk_mul_f32 v[94:95], v[94:95], v[94:95]
	v_pk_fma_f32 v[76:77], v[76:77], v[76:77], v[86:87]
	v_mov_b32_e32 v90, v47
	v_mov_b32_e32 v91, v39
	v_mov_b32_e32 v98, v42
	v_mov_b32_e32 v99, v34
	v_pk_fma_f32 v[86:87], v[92:93], v[92:93], v[94:95]
	v_pk_fma_f32 v[76:77], v[88:89], v[88:89], v[76:77]
	v_mov_b32_e32 v100, v43
	v_mov_b32_e32 v101, v35
	v_pk_fma_f32 v[86:87], v[98:99], v[98:99], v[86:87]
	v_pk_fma_f32 v[76:77], v[90:91], v[90:91], v[76:77]
	v_pk_fma_f32 v[86:87], v[100:101], v[100:101], v[86:87]
	v_add_f32_e32 v76, v76, v77
	v_add_f32_e32 v76, v76, v86
	v_add_f32_e32 v76, v76, v87
	s_nop 1
	v_add_f32_dpp v76, v76, v76 quad_perm:[1,0,3,2] row_mask:0xf bank_mask:0xf
	s_nop 1
	v_add_f32_dpp v76, v76, v76 quad_perm:[2,3,0,1] row_mask:0xf bank_mask:0xf
	s_nop 1
	v_add_f32_dpp v76, v76, v76 row_half_mirror row_mask:0xf bank_mask:0xf
	s_nop 1
	v_add_f32_dpp v76, v76, v76 row_mirror row_mask:0xf bank_mask:0xf
	s_nop 1
	v_add_f32_dpp v76, v76, v76 row_bcast:15 row_mask:0xa bank_mask:0xf
	s_nop 1
	v_add_f32_dpp v76, v76, v76 row_bcast:31 row_mask:0xc bank_mask:0xf
	s_nop 1
	v_readlane_b32 s100, v76, 63
	s_nop 3
	v_mov_b32_e32 v76, s100
	v_mov_b32_e32 v77, 0
	s_cbranch_vccnz .LBB0_142
	v_lshl_add_u64 v[86:87], v[72:73], 0, v[74:75]
	global_store_dwordx4 v[86:87], v[44:47], off

; DI void normmod_phase(const P& p, int layer, int which, int nrows, bool first, int vb, int nvb) {
;     ...
;   for (int row = row0; row < row1; ++row) {
;     const float* src;
;     float* res = row < LAT ? p.out + (size_t)row * 1024 : rh + (size_t)(row - LAT) * 1024;
;     if (first) src = row < LAT ? p.x + (size_t)row * 1024 : p.ctx + (size_t)(row - LAT) * 1024;
;     else src = res;
;     const int rg = row < LAT ? (row >> 11) : 8;
;     if (rg != crg) {
;       const float* mrow = mods + (size_t)rg * 9216;
; #pragma unroll
;       for (int i = 0; i < 4; ++i) {
;         sh[i] = *(const f32x4v*)(mrow + shift_i * 1024 + i * 256 + lane * 4);
;         sc1[i] = *(const f32x4v*)(mrow + scale_i * 1024 + i * 256 + lane * 4) + 1.f;
;         sc1[i] *= gg[i];
;       }
;       crg = rg;
;     }
;     f32x4v v[4];
;     float ss = 0.f;
; #pragma unroll
;     for (int i = 0; i < 4; ++i) {
;       v[i] = *(const f32x4v*)(src + i * 256 + lane * 4);
;       ss += v[i].x * v[i].x + v[i].y * v[i].y + v[i].z * v[i].z + v[i].w * v[i].w;
;     }
;     ss = wave_sum(ss);
;     const float rinv = rsqrtf(ss * (1.f / 1024.f) + EPS);
; #pragma unroll
;     for (int i = 0; i < 4; ++i) {
;       const int col = i * 256 + lane * 4;
;       if (first) *(f32x4v*)(res + col) = v[i];
;       const f32x4v y = v[i] * rinv * sc1[i] + sh[i];
;       uint2 o;
;       o.x = pack2(y.x, y.y); o.y = pack2(y.z, y.w);
;       *(uint2*)(dst + (size_t)row * 1024 + col) = o;
;     }
.LBB0_316:
	s_or_b64 exec, exec, s[42:43]
	v_cmp_gt_i32_e32 vcc, s8, v32
	v_add_u32_e32 v55, 0xffffc000, v32
	v_mov_b32_e32 v63, s69
	v_cndmask_b32_e32 v64, v55, v32, vcc
	v_mov_b32_e32 v55, s33
	v_cndmask_b32_e32 v65, 0, v33, vcc
	v_cndmask_b32_e32 v67, v55, v63, vcc
	v_mov_b32_e32 v55, s3
	v_mov_b32_e32 v63, s68
	v_cndmask_b32_e32 v66, v55, v63, vcc
	v_lshlrev_b64 v[64:65], 12, v[64:65]
	v_lshl_add_u64 v[64:65], v[66:67], 0, v[64:65]
	v_mov_b32_e32 v55, v96
	v_lshl_add_u64 v[54:55], v[64:65], 0, v[54:55]
	global_load_dwordx4 v[64:67], v[54:55], off
	global_load_dwordx4 v[68:71], v[54:55], off offset:1024
	global_load_dwordx4 v[224:227], v[54:55], off offset:2048
	global_load_dwordx4 v[228:231], v[54:55], off offset:3072
	v_lshl_add_u64 v[32:33], v[32:33], 0, 1
	s_mov_b64 s[16:17], 0x800
	s_waitcnt vmcnt(3)
	v_mov_b32_e32 v74, v65
	s_waitcnt vmcnt(2)
	v_mov_b32_e32 v75, v69
	v_mov_b32_e32 v72, v64
	v_mov_b32_e32 v73, v68
	v_pk_mul_f32 v[74:75], v[74:75], v[74:75]
	s_nop 0
	v_pk_fma_f32 v[72:73], v[72:73], v[72:73], v[74:75]
	v_mov_b32_e32 v74, v66
	v_mov_b32_e32 v75, v70
	v_pk_fma_f32 v[72:73], v[74:75], v[74:75], v[72:73]
	v_mov_b32_e32 v74, v67
	v_mov_b32_e32 v75, v71
	v_pk_fma_f32 v[80:81], v[74:75], v[74:75], v[72:73]
	v_add_f32_e32 v63, v80, v81
	s_waitcnt vmcnt(1)
	v_mov_b32_e32 v82, v225
	s_waitcnt vmcnt(0)
	v_mov_b32_e32 v83, v229
	v_mov_b32_e32 v54, v224
	v_mov_b32_e32 v55, v228
	v_pk_mul_f32 v[82:83], v[82:83], v[82:83]
	s_nop 0
	v_pk_fma_f32 v[54:55], v[54:55], v[54:55], v[82:83]
	v_mov_b32_e32 v82, v226
	v_mov_b32_e32 v83, v230
	v_pk_fma_f32 v[54:55], v[82:83], v[82:83], v[54:55]
	v_mov_b32_e32 v82, v227
	v_mov_b32_e32 v83, v231
	v_pk_fma_f32 v[54:55], v[82:83], v[82:83], v[54:55]
	s_nop 0
	v_add_f32_e32 v54, v63, v54
	v_add_f32_e32 v54, v54, v55
	s_nop 1
	v_add_f32_dpp v54, v54, v54 quad_perm:[1,0,3,2] row_mask:0xf bank_mask:0xf
	s_nop 1
	v_add_f32_dpp v54, v54, v54 quad_perm:[2,3,0,1] row_mask:0xf bank_mask:0xf
	s_nop 1
	v_add_f32_dpp v54, v54, v54 row_half_mirror row_mask:0xf bank_mask:0xf
	s_nop 1
	v_add_f32_dpp v54, v54, v54 row_mirror row_mask:0xf bank_mask:0xf
	s_nop 1
	v_add_f32_dpp v54, v54, v54 row_bcast:15 row_mask:0xa bank_mask:0xf
	s_nop 1
	v_add_f32_dpp v54, v54, v54 row_bcast:31 row_mask:0xc bank_mask:0xf
	s_nop 1
	v_readlane_b32 s100, v54, 63
	s_nop 3
	v_mov_b32_e32 v54, s100
	v_fmamk_f32 v54, v54, 0x3a800000, v119
	v_cmp_gt_f32_e32 vcc, s9, v54
	v_mul_f32_e32 v55, 0x4b800000, v54
	s_nop 0
	v_cndmask_b32_e32 v54, v54, v55, vcc
	v_rsq_f32_e32 v54, v54
	s_nop 0
	v_mul_f32_e32 v55, 0x45800000, v54
	v_cndmask_b32_e32 v54, v54, v55, vcc
	v_pk_mul_f32 v[64:65], v[64:65], v[54:55] op_sel_hi:[1,0]
	v_pk_mul_f32 v[66:67], v[66:67], v[54:55] op_sel_hi:[1,0]
	v_pk_fma_f32 v[64:65], v[38:39], v[64:65], v[28:29]
	v_pk_fma_f32 v[66:67], v[48:49], v[66:67], v[30:31]
	v_cvt_pk_bf16_f32 v64, v64, v65
	v_cvt_pk_bf16_f32 v65, v66, v67
	global_store_dwordx2 v[36:37], v[64:65], off
	v_pk_mul_f32 v[64:65], v[68:69], v[54:55] op_sel_hi:[1,0]
	v_pk_mul_f32 v[66:67], v[70:71], v[54:55] op_sel_hi:[1,0]
	v_pk_fma_f32 v[64:65], v[40:41], v[64:65], v[24:25]
	v_pk_fma_f32 v[66:67], v[42:43], v[66:67], v[26:27]
	v_cvt_pk_bf16_f32 v64, v64, v65
	v_cvt_pk_bf16_f32 v65, v66, v67
	global_store_dwordx2 v[36:37], v[64:65], off offset:512
	v_pk_mul_f32 v[64:65], v[224:225], v[54:55] op_sel_hi:[1,0]
	v_pk_mul_f32 v[66:67], v[226:227], v[54:55] op_sel_hi:[1,0]
	v_pk_fma_f32 v[64:65], v[44:45], v[64:65], v[20:21]
	v_pk_fma_f32 v[66:67], v[46:47], v[66:67], v[22:23]
	v_cvt_pk_bf16_f32 v64, v64, v65
	v_cvt_pk_bf16_f32 v65, v66, v67
	global_store_dwordx2 v[36:37], v[64:65], off offset:1024
	v_pk_mul_f32 v[64:65], v[228:229], v[54:55] op_sel_hi:[1,0]
	v_pk_mul_f32 v[54:55], v[230:231], v[54:55] op_sel_hi:[1,0]
	v_pk_fma_f32 v[64:65], v[50:51], v[64:65], v[16:17]
	v_pk_fma_f32 v[54:55], v[52:53], v[54:55], v[18:19]
	v_cvt_pk_bf16_f32 v64, v64, v65
	v_cvt_pk_bf16_f32 v65, v54, v55
	v_cmp_ge_i32_e32 vcc, v32, v35
	global_store_dwordx2 v[36:37], v[64:65], off offset:1536
	v_lshl_add_u64 v[36:37], v[36:37], 0, s[16:17]
	s_or_b64 s[38:39], vcc, s[38:39]
	s_andn2_b64 exec, exec, s[38:39]
	s_cbranch_execz .LBB0_319

; DI void normmod_phase(const P& p, int layer, int which, int nrows, bool first, int vb, int nvb) {
;     ...
;   for (int row = row0; row < row1; ++row) {
;     const float* src;
;     float* res = row < LAT ? p.out + (size_t)row * 1024 : rh + (size_t)(row - LAT) * 1024;
;     if (first) src = row < LAT ? p.x + (size_t)row * 1024 : p.ctx + (size_t)(row - LAT) * 1024;
;     else src = res;
;     const int rg = row < LAT ? (row >> 11) : 8;
;     if (rg != crg) {
;       const float* mrow = mods + (size_t)rg * 9216;
; #pragma unroll
;       for (int i = 0; i < 4; ++i) {
;         sh[i] = *(const f32x4v*)(mrow + shift_i * 1024 + i * 256 + lane * 4);
;         sc1[i] = *(const f32x4v*)(mrow + scale_i * 1024 + i * 256 + lane * 4) + 1.f;
;         sc1[i] *= gg[i];
;       }
;       crg = rg;
;     }
;     f32x4v v[4];
;     float ss = 0.f;
; #pragma unroll
;     for (int i = 0; i < 4; ++i) {
;       v[i] = *(const f32x4v*)(src + i * 256 + lane * 4);
;       ss += v[i].x * v[i].x + v[i].y * v[i].y + v[i].z * v[i].z + v[i].w * v[i].w;
;     }
;     ss = wave_sum(ss);
;     const float rinv = rsqrtf(ss * (1.f / 1024.f) + EPS);
; #pragma unroll
;     for (int i = 0; i < 4; ++i) {
;       const int col = i * 256 + lane * 4;
;       if (first) *(f32x4v*)(res + col) = v[i];
;       const f32x4v y = v[i] * rinv * sc1[i] + sh[i];
;       uint2 o;
;       o.x = pack2(y.x, y.y); o.y = pack2(y.z, y.w);
;       *(uint2*)(dst + (size_t)row * 1024 + col) = o;
;     }
.LBB0_1350:
	s_or_b64 exec, exec, s[40:41]
	v_cmp_gt_i32_e32 vcc, s8, v32
	v_add_u32_e32 v55, 0xffffc000, v32
	v_mov_b32_e32 v63, s69
	v_cndmask_b32_e32 v64, v55, v32, vcc
	v_mov_b32_e32 v55, s33
	v_cndmask_b32_e32 v65, 0, v33, vcc
	v_cndmask_b32_e32 v67, v55, v63, vcc
	v_mov_b32_e32 v55, s3
	v_mov_b32_e32 v63, s68
	v_cndmask_b32_e32 v66, v55, v63, vcc
	v_lshlrev_b64 v[64:65], 12, v[64:65]
	v_lshl_add_u64 v[64:65], v[66:67], 0, v[64:65]
	v_mov_b32_e32 v55, v96
	v_lshl_add_u64 v[54:55], v[64:65], 0, v[54:55]
	global_load_dwordx4 v[64:67], v[54:55], off
	global_load_dwordx4 v[68:71], v[54:55], off offset:1024
	global_load_dwordx4 v[224:227], v[54:55], off offset:2048
	global_load_dwordx4 v[228:231], v[54:55], off offset:3072
	v_lshl_add_u64 v[32:33], v[32:33], 0, 1
	s_mov_b64 s[16:17], 0x800
	s_waitcnt vmcnt(3)
	v_mov_b32_e32 v74, v65
	s_waitcnt vmcnt(2)
	v_mov_b32_e32 v75, v69
	v_mov_b32_e32 v72, v64
	v_mov_b32_e32 v73, v68
	v_pk_mul_f32 v[74:75], v[74:75], v[74:75]
	s_nop 0
	v_pk_fma_f32 v[72:73], v[72:73], v[72:73], v[74:75]
	v_mov_b32_e32 v74, v66
	v_mov_b32_e32 v75, v70
	v_pk_fma_f32 v[72:73], v[74:75], v[74:75], v[72:73]
	v_mov_b32_e32 v74, v67
	v_mov_b32_e32 v75, v71
	v_pk_fma_f32 v[80:81], v[74:75], v[74:75], v[72:73]
	v_add_f32_e32 v63, v80, v81
	s_waitcnt vmcnt(1)
	v_mov_b32_e32 v82, v225
	s_waitcnt vmcnt(0)
	v_mov_b32_e32 v83, v229
	v_mov_b32_e32 v54, v224
	v_mov_b32_e32 v55, v228
	v_pk_mul_f32 v[82:83], v[82:83], v[82:83]
	s_nop 0
	v_pk_fma_f32 v[54:55], v[54:55], v[54:55], v[82:83]
	v_mov_b32_e32 v82, v226
	v_mov_b32_e32 v83, v230
	v_pk_fma_f32 v[54:55], v[82:83], v[82:83], v[54:55]
	v_mov_b32_e32 v82, v227
	v_mov_b32_e32 v83, v231
	v_pk_fma_f32 v[54:55], v[82:83], v[82:83], v[54:55]
	s_nop 0
	v_add_f32_e32 v54, v63, v54
	v_add_f32_e32 v54, v54, v55
	s_nop 1
	v_add_f32_dpp v54, v54, v54 quad_perm:[1,0,3,2] row_mask:0xf bank_mask:0xf
	s_nop 1
	v_add_f32_dpp v54, v54, v54 quad_perm:[2,3,0,1] row_mask:0xf bank_mask:0xf
	s_nop 1
	v_add_f32_dpp v54, v54, v54 row_half_mirror row_mask:0xf bank_mask:0xf
	s_nop 1
	v_add_f32_dpp v54, v54, v54 row_mirror row_mask:0xf bank_mask:0xf
	s_nop 1
	v_add_f32_dpp v54, v54, v54 row_bcast:15 row_mask:0xa bank_mask:0xf
	s_nop 1
	v_add_f32_dpp v54, v54, v54 row_bcast:31 row_mask:0xc bank_mask:0xf
	s_nop 1
	v_readlane_b32 s100, v54, 63
	s_nop 3
	v_mov_b32_e32 v54, s100
	v_fmamk_f32 v54, v54, 0x3a800000, v119
	v_cmp_gt_f32_e32 vcc, s9, v54
	v_mul_f32_e32 v55, 0x4b800000, v54
	s_nop 0
	v_cndmask_b32_e32 v54, v54, v55, vcc
	v_rsq_f32_e32 v54, v54
	s_nop 0
	v_mul_f32_e32 v55, 0x45800000, v54
	v_cndmask_b32_e32 v54, v54, v55, vcc
	v_pk_mul_f32 v[64:65], v[64:65], v[54:55] op_sel_hi:[1,0]
	v_pk_mul_f32 v[66:67], v[66:67], v[54:55] op_sel_hi:[1,0]
	v_pk_fma_f32 v[64:65], v[38:39], v[64:65], v[28:29]
	v_pk_fma_f32 v[66:67], v[48:49], v[66:67], v[30:31]
	v_cvt_pk_bf16_f32 v64, v64, v65
	v_cvt_pk_bf16_f32 v65, v66, v67
	global_store_dwordx2 v[36:37], v[64:65], off
	v_pk_mul_f32 v[64:65], v[68:69], v[54:55] op_sel_hi:[1,0]
	v_pk_mul_f32 v[66:67], v[70:71], v[54:55] op_sel_hi:[1,0]
	v_pk_fma_f32 v[64:65], v[40:41], v[64:65], v[24:25]
	v_pk_fma_f32 v[66:67], v[42:43], v[66:67], v[26:27]
	v_cvt_pk_bf16_f32 v64, v64, v65
	v_cvt_pk_bf16_f32 v65, v66, v67
	global_store_dwordx2 v[36:37], v[64:65], off offset:512
	v_pk_mul_f32 v[64:65], v[224:225], v[54:55] op_sel_hi:[1,0]
	v_pk_mul_f32 v[66:67], v[226:227], v[54:55] op_sel_hi:[1,0]
	v_pk_fma_f32 v[64:65], v[44:45], v[64:65], v[20:21]
	v_pk_fma_f32 v[66:67], v[46:47], v[66:67], v[22:23]
	v_cvt_pk_bf16_f32 v64, v64, v65
	v_cvt_pk_bf16_f32 v65, v66, v67
	global_store_dwordx2 v[36:37], v[64:65], off offset:1024
	v_pk_mul_f32 v[64:65], v[228:229], v[54:55] op_sel_hi:[1,0]
	v_pk_mul_f32 v[54:55], v[230:231], v[54:55] op_sel_hi:[1,0]
	v_pk_fma_f32 v[64:65], v[50:51], v[64:65], v[16:17]
	v_pk_fma_f32 v[54:55], v[52:53], v[54:55], v[18:19]
	v_cvt_pk_bf16_f32 v64, v64, v65
	v_cvt_pk_bf16_f32 v65, v54, v55
	v_cmp_ge_i32_e32 vcc, v32, v35
	global_store_dwordx2 v[36:37], v[64:65], off offset:1536
	v_lshl_add_u64 v[36:37], v[36:37], 0, s[16:17]
	s_or_b64 s[38:39], vcc, s[38:39]
	s_andn2_b64 exec, exec, s[38:39]
	s_cbranch_execz .LBB0_1353
